# v15 plus SWA band masks computed with one subtract and one unsigned compare per element (instruction selection, identical masks)
# speedup vs baseline: 1.0026x; 1.0026x over previous
.LBB0_255:
	v_add_u32_e32 v36, v89, v69
	v_mov_b32_e32 v94, v32
	v_lshlrev_b64 v[32:33], 1, v[64:65]
	v_mad_i64_i32 v[36:37], s[0:1], v36, s55, v[82:83]
	v_add_u32_e32 v34, 16, v64
	v_mov_b32_e32 v35, v65
	v_lshl_add_u64 v[38:39], v[84:85], 0, v[32:33]
	v_lshl_add_u64 v[32:33], v[86:87], 0, v[32:33]
	v_lshl_add_u64 v[36:37], v[36:37], 0, v[76:77]
	v_lshl_add_u64 v[34:35], v[34:35], 1, v[86:87]
	global_load_dwordx2 v[96:97], v[38:39], off
	global_load_dwordx2 v[98:99], v[38:39], off offset:16
	global_load_dwordx2 v[100:101], v[38:39], off offset:32
	global_load_dwordx2 v[102:103], v[38:39], off offset:48
	global_load_dwordx2 v[104:105], v[32:33], off
	global_load_dwordx2 v[106:107], v[32:33], off offset:16
	global_load_dwordx2 v[108:109], v[34:35], off
	global_load_dwordx2 v[110:111], v[34:35], off offset:16
	v_add_co_u32_e64 v32, s[0:1], s33, v36
	v_lshl_add_u64 v[120:121], v[36:37], 0, s[42:43]
	s_nop 0
	v_addc_co_u32_e64 v33, s[0:1], 0, v37, s[0:1]
	global_load_dwordx4 v[32:35], v[32:33], off
	s_nop 0
	global_load_dwordx4 v[112:115], v[120:121], off offset:32
	global_load_dwordx4 v[116:119], v[120:121], off offset:96
	v_add_u32_e32 v40, v89, v75
	v_add_u32_e32 v154, s56, v40
	v_add_u32_e32 v154, -1, v154
	v_lshl_add_u32 v156, s56, 1, -1
	global_load_dwordx4 v[120:123], v[120:121], off offset:64
	s_waitcnt vmcnt(19)
	s_waitcnt vmcnt(18)
	v_subrev_u32_e32 v149, 0, v154
	v_subrev_u32_e32 v150, 1, v154
	v_subrev_u32_e32 v151, 2, v154
	v_add_u32_e32 v71, 1, v71
	v_cmp_ge_u32_e32 vcc, v71, v73
	v_subrev_u32_e32 v95, 3, v154
	s_or_b64 s[50:51], vcc, s[50:51]
	v_cmp_gt_u32_e32 vcc, v156, v150
	v_cmp_gt_u32_e64 s[2:3], v156, v95
	v_cmp_gt_u32_e64 s[28:29], v156, v149
	v_cmp_gt_u32_e64 s[0:1], v156, v151
	v_subrev_u32_e32 v124, 16, v154
	v_cmp_gt_u32_e64 s[12:13], v156, v124
	v_subrev_u32_e32 v75, 32, v75
	v_add_u32_e32 v64, 32, v64
	v_add_u32_e32 v69, 32, v69
	s_waitcnt vmcnt(3)
	v_mfma_f32_32x32x16_bf16 v[32:47], v[32:35], v[48:51], 0
	s_waitcnt vmcnt(2)
	v_mfma_f32_32x32x16_bf16 v[32:47], v[112:115], v[52:55], v[32:47]
	v_subrev_u32_e32 v112, 8, v154
	v_cmp_gt_u32_e64 s[4:5], v156, v112
	v_subrev_u32_e32 v113, 9, v154
	v_subrev_u32_e32 v114, 10, v154
	v_subrev_u32_e32 v115, 11, v154
	v_cmp_gt_u32_e64 s[6:7], v156, v113
	v_cmp_gt_u32_e64 s[8:9], v156, v114
	s_waitcnt vmcnt(0)
	v_mfma_f32_32x32x16_bf16 v[32:47], v[120:123], v[56:59], v[32:47]
	v_subrev_u32_e32 v125, 17, v154
	v_cmp_gt_u32_e64 s[10:11], v156, v115
	v_subrev_u32_e32 v120, 18, v154
	v_subrev_u32_e32 v121, 19, v154
	v_cmp_gt_u32_e64 s[14:15], v156, v125
	v_subrev_u32_e32 v122, 24, v154
	v_subrev_u32_e32 v123, 25, v154
	v_mfma_f32_32x32x16_bf16 v[32:47], v[116:119], v[60:63], v[32:47]
	v_cmp_gt_u32_e64 s[16:17], v156, v120
	v_cmp_gt_u32_e64 s[18:19], v156, v121
	v_subrev_u32_e32 v126, 26, v154
	v_subrev_u32_e32 v127, 27, v154
	v_cmp_gt_u32_e64 s[20:21], v156, v122
	v_cmp_gt_u32_e64 s[22:23], v156, v123
	v_cmp_gt_u32_e64 s[24:25], v156, v126
	s_nop 4
	v_max_f32_e32 v95, v32, v32
	v_cndmask_b32_e32 v112, v93, v33, vcc
	v_max_f32_e32 v95, 0xf149f2ca, v95
	v_max_f32_e32 v112, v112, v112
	v_cndmask_b32_e64 v95, v93, v95, s[28:29]
	v_cndmask_b32_e64 v113, v93, v34, s[0:1]
	v_cndmask_b32_e64 v114, v93, v35, s[2:3]
	v_max_f32_e32 v95, v95, v112
	v_cndmask_b32_e64 v115, v93, v36, s[4:5]
	v_cndmask_b32_e64 v116, v93, v37, s[6:7]
	v_max3_f32 v95, v95, v113, v114
	v_cndmask_b32_e64 v117, v93, v38, s[8:9]
	v_cndmask_b32_e64 v118, v93, v39, s[10:11]
	v_max3_f32 v95, v95, v115, v116
	v_cndmask_b32_e64 v119, v93, v40, s[12:13]
	v_cndmask_b32_e64 v120, v93, v41, s[14:15]
	v_max3_f32 v95, v95, v117, v118
	v_cndmask_b32_e64 v121, v93, v42, s[16:17]
	v_cndmask_b32_e64 v122, v93, v43, s[18:19]
	v_max3_f32 v95, v95, v119, v120
	v_cmp_gt_u32_e64 s[26:27], v156, v127
	v_cndmask_b32_e64 v123, v93, v44, s[20:21]
	v_cndmask_b32_e64 v124, v93, v45, s[22:23]
	v_max3_f32 v95, v95, v121, v122
	v_cndmask_b32_e64 v125, v93, v46, s[24:25]
	v_cndmask_b32_e64 v126, v93, v47, s[26:27]
	v_max3_f32 v95, v95, v123, v124
	v_max3_f32 v95, v95, v125, v126
	v_mov_b32_e32 v112, v95
	s_nop 1
	v_permlane32_swap_b32_e32 v95, v112
	v_max3_f32 v95, v81, v95, v112
	v_sub_f32_e32 v32, v32, v95
	v_sub_f32_e32 v33, v33, v95
	v_sub_f32_e32 v34, v34, v95
	v_sub_f32_e32 v35, v35, v95
	v_sub_f32_e32 v36, v36, v95
	v_sub_f32_e32 v37, v37, v95
	v_sub_f32_e32 v38, v38, v95
	v_sub_f32_e32 v39, v39, v95
	v_sub_f32_e32 v112, v81, v95
	v_mul_f32_e32 v32, 0x3fb8aa3b, v32
	v_mul_f32_e32 v33, 0x3fb8aa3b, v33
	v_mul_f32_e32 v34, 0x3fb8aa3b, v34
	v_mul_f32_e32 v35, 0x3fb8aa3b, v35
	v_mul_f32_e32 v36, 0x3fb8aa3b, v36
	v_mul_f32_e32 v37, 0x3fb8aa3b, v37
	v_mul_f32_e32 v38, 0x3fb8aa3b, v38
	v_mul_f32_e32 v39, 0x3fb8aa3b, v39
	v_sub_f32_e32 v40, v40, v95
	v_sub_f32_e32 v41, v41, v95
	v_sub_f32_e32 v42, v42, v95
	v_sub_f32_e32 v43, v43, v95
	v_sub_f32_e32 v44, v44, v95
	v_sub_f32_e32 v45, v45, v95
	v_sub_f32_e32 v46, v46, v95
	v_sub_f32_e32 v47, v47, v95
	v_mov_b32_e32 v81, v95
	v_mul_f32_e32 v95, 0x3fb8aa3b, v112
	v_exp_f32_e32 v32, v32
	v_exp_f32_e32 v33, v33
	v_exp_f32_e32 v34, v34
	v_exp_f32_e32 v35, v35
	v_exp_f32_e32 v112, v36
	v_exp_f32_e32 v37, v37
	v_exp_f32_e32 v38, v38
	v_exp_f32_e32 v39, v39
	v_exp_f32_e32 v36, v95
	v_cndmask_b32_e64 v95, 0, v32, s[28:29]
	v_cndmask_b32_e32 v113, 0, v33, vcc
	v_cndmask_b32_e64 v114, 0, v34, s[0:1]
	v_cndmask_b32_e64 v115, 0, v35, s[2:3]
	v_cndmask_b32_e64 v112, 0, v112, s[4:5]
	v_cndmask_b32_e64 v37, 0, v37, s[6:7]
	v_cndmask_b32_e64 v38, 0, v38, s[8:9]
	v_cndmask_b32_e64 v39, 0, v39, s[10:11]
	v_pk_mul_f32 v[14:15], v[14:15], v[36:37] op_sel_hi:[1,0]
	v_pk_mul_f32 v[12:13], v[12:13], v[36:37] op_sel_hi:[1,0]
	v_pk_mul_f32 v[10:11], v[10:11], v[36:37] op_sel_hi:[1,0]
	v_pk_mul_f32 v[8:9], v[8:9], v[36:37] op_sel_hi:[1,0]
	v_pk_mul_f32 v[6:7], v[6:7], v[36:37] op_sel_hi:[1,0]
	v_pk_mul_f32 v[4:5], v[4:5], v[36:37] op_sel_hi:[1,0]
	v_pk_mul_f32 v[2:3], v[2:3], v[36:37] op_sel_hi:[1,0]
	v_pk_mul_f32 v[0:1], v[0:1], v[36:37] op_sel_hi:[1,0]
	v_pk_mul_f32 v[30:31], v[30:31], v[36:37] op_sel_hi:[1,0]
	v_cvt_pk_bf16_f32 v32, v95, v113
	v_cvt_pk_bf16_f32 v33, v114, v115
	v_cvt_pk_bf16_f32 v34, v112, v37
	v_cvt_pk_bf16_f32 v35, v38, v39
	v_pk_mul_f32 v[28:29], v[28:29], v[36:37] op_sel_hi:[1,0]
	v_pk_mul_f32 v[26:27], v[26:27], v[36:37] op_sel_hi:[1,0]
	v_pk_mul_f32 v[24:25], v[24:25], v[36:37] op_sel_hi:[1,0]
	v_pk_mul_f32 v[22:23], v[22:23], v[36:37] op_sel_hi:[1,0]
	v_pk_mul_f32 v[20:21], v[20:21], v[36:37] op_sel_hi:[1,0]
	v_pk_mul_f32 v[18:19], v[18:19], v[36:37] op_sel_hi:[1,0]
	v_pk_mul_f32 v[16:17], v[16:17], v[36:37] op_sel_hi:[1,0]
	v_add_f32_e32 v95, 0, v95
	v_mfma_f32_32x32x16_bf16 v[0:15], v[96:99], v[32:35], v[0:15]
	v_add_f32_e32 v95, v113, v95
	v_mul_f32_e32 v40, 0x3fb8aa3b, v40
	v_mul_f32_e32 v41, 0x3fb8aa3b, v41
	v_mul_f32_e32 v42, 0x3fb8aa3b, v42
	v_mul_f32_e32 v43, 0x3fb8aa3b, v43
	v_mul_f32_e32 v44, 0x3fb8aa3b, v44
	v_mul_f32_e32 v45, 0x3fb8aa3b, v45
	v_mfma_f32_32x32x16_bf16 v[16:31], v[104:107], v[32:35], v[16:31]
	v_mul_f32_e32 v46, 0x3fb8aa3b, v46
	v_mul_f32_e32 v47, 0x3fb8aa3b, v47
	v_add_f32_e32 v95, v114, v95
	v_exp_f32_e32 v40, v40
	v_exp_f32_e32 v41, v41
	v_exp_f32_e32 v42, v42
	v_exp_f32_e32 v43, v43
	v_exp_f32_e32 v44, v44
	v_exp_f32_e32 v45, v45
	v_exp_f32_e32 v46, v46
	v_exp_f32_e32 v47, v47
	v_add_f32_e32 v95, v115, v95
	v_add_f32_e32 v95, v112, v95
	v_add_f32_e32 v37, v37, v95
	v_add_f32_e32 v37, v38, v37
	v_cndmask_b32_e64 v40, 0, v40, s[12:13]
	v_cndmask_b32_e64 v41, 0, v41, s[14:15]
	v_cndmask_b32_e64 v42, 0, v42, s[16:17]
	v_cndmask_b32_e64 v43, 0, v43, s[18:19]
	v_cndmask_b32_e64 v44, 0, v44, s[20:21]
	v_cndmask_b32_e64 v45, 0, v45, s[22:23]
	v_cndmask_b32_e64 v46, 0, v46, s[24:25]
	v_cndmask_b32_e64 v47, 0, v47, s[26:27]
	v_add_f32_e32 v37, v39, v37
	v_cvt_pk_bf16_f32 v32, v40, v41
	v_cvt_pk_bf16_f32 v33, v42, v43
	v_cvt_pk_bf16_f32 v34, v44, v45
	v_cvt_pk_bf16_f32 v35, v46, v47
	v_add_f32_e32 v37, v40, v37
	v_add_f32_e32 v37, v41, v37
	v_mfma_f32_32x32x16_bf16 v[0:15], v[100:103], v[32:35], v[0:15]
	v_mfma_f32_32x32x16_bf16 v[16:31], v[108:111], v[32:35], v[16:31]
	v_add_f32_e32 v32, v42, v37
	v_add_f32_e32 v32, v43, v32
	v_add_f32_e32 v32, v44, v32
	v_add_f32_e32 v32, v45, v32
	v_add_f32_e32 v32, v46, v32
	v_add_f32_e32 v32, v47, v32
	v_fmac_f32_e32 v32, v94, v36
	s_andn2_b64 exec, exec, s[50:51]
	s_cbranch_execnz .LBB0_255
	s_or_b64 exec, exec, s[50:51]
	s_branch .LBB0_252
